# v9 + hand-written gate/up epilogue: g*u*rcp((1+exp2(g*c))*w) regrouping (12 fewer packed multiplies per 8 outputs), lane-group sums by permlane16/32 swaps instead of ds_bpermute, all ssq loads up fron
# speedup vs baseline: 1.0146x; 1.0063x over previous
; __device__ __forceinline__ unsigned pk2(float lo, float hi) { f32x2_t v = {lo, hi}; bf16x2_t b = __builtin_convertvector(v, bf16x2_t); return __builtin_bit_cast(unsigned, b); }
; __device__ __forceinline__ float sigm(float x) { return frcp(1.f + fexp2(-LOG2E * x)); }
;   __device__ __forceinline__ void operator()(const pg8::f32x4 (&acc)[2][2][4][2], const pg8::Unit& u, int wr, int wc, int fr, int fq) const {
;     int z; asm volatile("v_mov_b32 %0, 0" : "=v"(z));
;     const int row0 = u.pm * 256 + wr * 64 + fr + z, col0 = u.pn * 128 + wc * 32 + 8 * fq + z;
; #pragma unroll
;     for (int ai = 0; ai < 2; ++ai) {
;       float rs[4];
; #pragma unroll
;       for (int m = 0; m < 4; ++m) { const f32x4 a = *(const f32x4*)(ssq + (unsigned)(row0 + ai * 128 + m * 16) * 16 + 4 * fq); rs[m] = (a[0] + a[1]) + (a[2] + a[3]); }
; #pragma unroll
;       for (int m = 0; m < 4; ++m) { float v = rs[m]; v += __shfl_xor(v, 16); v += __shfl_xor(v, 32); rs[m] = rsqrtf(v * (1.f / 1024.f) + EPS); }
; #pragma unroll
;       for (int m = 0; m < 4; ++m) {
;         const float r = rs[m]; float v[8];
; #pragma unroll
;         for (int n = 0; n < 2; ++n)
; #pragma unroll
;           for (int c = 0; c < 4; ++c) { const float g = acc[ai][0][m][n][c] * r, uu = acc[ai][1][m][n][c] * r; v[4 * n + c] = g * sigm(g) * uu; }
;         u32x4 w; w.x = pk2(v[0], v[1]); w.y = pk2(v[2], v[3]); w.z = pk2(v[4], v[5]); w.w = pk2(v[6], v[7]);
;         *(u32x4*)(hbuf + (unsigned)(row0 + ai * 128 + m * 16) * DFF + col0) = w;
.LBB0_184:
	s_lshl_b32 s4, s4, 8
	s_mov_b32 s98, 0x3a800000
	s_mov_b32 s100, 0xb0000
	s_mov_b32 s101, 0
	v_add_u32_e32 v148, s4, v151
	v_lshlrev_b32_e32 v136, 4, v148
	v_lshl_add_u64 v[242:243], v[136:137], 2, v[138:139]
	global_load_dwordx4 v[172:175], v[242:243], off
	global_load_dwordx4 v[176:179], v[242:243], off offset:1024
	global_load_dwordx4 v[180:183], v[242:243], off offset:2048
	global_load_dwordx4 v[184:187], v[242:243], off offset:3072
	v_add_u32_e32 v136, 0x800, v136
	v_lshl_add_u64 v[242:243], v[136:137], 2, v[138:139]
	global_load_dwordx4 v[188:191], v[242:243], off
	global_load_dwordx4 v[192:195], v[242:243], off offset:1024
	global_load_dwordx4 v[196:199], v[242:243], off offset:2048
	global_load_dwordx4 v[200:203], v[242:243], off offset:3072
	v_lshl_or_b32 v152, s5, 7, v154
	v_mul_u32_u24_e32 v136, 0xb00, v148
	v_add_u32_e32 v136, v136, v152
	v_lshl_add_u64 v[240:241], v[136:137], 1, s[38:39]
	v_mov_b32_e32 v150, 0x358637bd
	v_lshl_add_u64 v[242:243], v[240:241], 0, s[100:101]
	s_mov_b32 s100, 0x16000
	s_waitcnt vmcnt(0)
	v_add_f32_e32 v204, v172, v173
	v_add_f32_e32 v228, v174, v175
	v_add_f32_e32 v205, v176, v177
	v_add_f32_e32 v229, v178, v179
	v_add_f32_e32 v206, v180, v181
	v_add_f32_e32 v230, v182, v183
	v_add_f32_e32 v207, v184, v185
	v_add_f32_e32 v231, v186, v187
	v_add_f32_e32 v208, v188, v189
	v_add_f32_e32 v232, v190, v191
	v_add_f32_e32 v209, v192, v193
	v_add_f32_e32 v233, v194, v195
	v_add_f32_e32 v210, v196, v197
	v_add_f32_e32 v234, v198, v199
	v_add_f32_e32 v211, v200, v201
	v_add_f32_e32 v235, v202, v203
	v_add_f32_e32 v204, v204, v228
	v_add_f32_e32 v205, v205, v229
	v_add_f32_e32 v206, v206, v230
	v_add_f32_e32 v207, v207, v231
	v_add_f32_e32 v208, v208, v232
	v_add_f32_e32 v209, v209, v233
	v_add_f32_e32 v210, v210, v234
	v_add_f32_e32 v211, v211, v235
	v_mov_b32_e32 v228, v204
	v_mov_b32_e32 v229, v205
	v_mov_b32_e32 v230, v206
	v_mov_b32_e32 v231, v207
	v_mov_b32_e32 v232, v208
	v_mov_b32_e32 v233, v209
	v_mov_b32_e32 v234, v210
	v_mov_b32_e32 v235, v211
	v_permlane16_swap_b32_e32 v204, v228
	v_permlane16_swap_b32_e32 v205, v229
	v_permlane16_swap_b32_e32 v206, v230
	v_permlane16_swap_b32_e32 v207, v231
	v_permlane16_swap_b32_e32 v208, v232
	v_permlane16_swap_b32_e32 v209, v233
	v_permlane16_swap_b32_e32 v210, v234
	v_permlane16_swap_b32_e32 v211, v235
	v_add_f32_e32 v204, v204, v228
	v_add_f32_e32 v205, v205, v229
	v_add_f32_e32 v206, v206, v230
	v_add_f32_e32 v207, v207, v231
	v_add_f32_e32 v208, v208, v232
	v_add_f32_e32 v209, v209, v233
	v_add_f32_e32 v210, v210, v234
	v_add_f32_e32 v211, v211, v235
	v_mov_b32_e32 v228, v204
	v_mov_b32_e32 v229, v205
	v_mov_b32_e32 v230, v206
	v_mov_b32_e32 v231, v207
	v_mov_b32_e32 v232, v208
	v_mov_b32_e32 v233, v209
	v_mov_b32_e32 v234, v210
	v_mov_b32_e32 v235, v211
	v_permlane32_swap_b32_e32 v204, v228
	v_permlane32_swap_b32_e32 v205, v229
	v_permlane32_swap_b32_e32 v206, v230
	v_permlane32_swap_b32_e32 v207, v231
	v_permlane32_swap_b32_e32 v208, v232
	v_permlane32_swap_b32_e32 v209, v233
	v_permlane32_swap_b32_e32 v210, v234
	v_permlane32_swap_b32_e32 v211, v235
	v_add_f32_e32 v204, v204, v228
	v_add_f32_e32 v205, v205, v229
	v_add_f32_e32 v206, v206, v230
	v_add_f32_e32 v207, v207, v231
	v_add_f32_e32 v208, v208, v232
	v_add_f32_e32 v209, v209, v233
	v_add_f32_e32 v210, v210, v234
	v_add_f32_e32 v211, v211, v235
	v_fma_f32 v172, v204, s98, v150
	v_fma_f32 v174, v205, s98, v150
	v_fma_f32 v176, v206, s98, v150
	v_fma_f32 v178, v207, s98, v150
	v_fma_f32 v180, v208, s98, v150
	v_fma_f32 v182, v209, s98, v150
	v_fma_f32 v184, v210, s98, v150
	v_fma_f32 v186, v211, s98, v150
	v_rsq_f32_e32 v188, v172
	v_rsq_f32_e32 v190, v174
	v_rsq_f32_e32 v192, v176
	v_rsq_f32_e32 v194, v178
	v_rsq_f32_e32 v196, v180
	v_rsq_f32_e32 v198, v182
	v_rsq_f32_e32 v200, v184
	v_rsq_f32_e32 v202, v186
	v_mul_f32_e32 v188, 0xbfb8aa3b, v188
	v_mul_f32_e32 v190, 0xbfb8aa3b, v190
	v_mul_f32_e32 v192, 0xbfb8aa3b, v192
	v_mul_f32_e32 v194, 0xbfb8aa3b, v194
	v_mul_f32_e32 v196, 0xbfb8aa3b, v196
	v_mul_f32_e32 v198, 0xbfb8aa3b, v198
	v_mul_f32_e32 v200, 0xbfb8aa3b, v200
	v_mul_f32_e32 v202, 0xbfb8aa3b, v202
	v_pk_mul_f32 v[228:229], v[124:125], v[188:189] op_sel_hi:[1,0]
	v_pk_mul_f32 v[230:231], v[126:127], v[188:189] op_sel_hi:[1,0]
	v_pk_mul_f32 v[232:233], v[116:117], v[188:189] op_sel_hi:[1,0]
	v_pk_mul_f32 v[234:235], v[118:119], v[188:189] op_sel_hi:[1,0]
	v_exp_f32_e32 v228, v228
	v_exp_f32_e32 v229, v229
	v_exp_f32_e32 v230, v230
	v_exp_f32_e32 v231, v231
	v_exp_f32_e32 v232, v232
	v_exp_f32_e32 v233, v233
	v_exp_f32_e32 v234, v234
	v_exp_f32_e32 v235, v235
	v_pk_mul_f32 v[124:125], v[124:125], v[120:121]
	v_pk_mul_f32 v[126:127], v[126:127], v[122:123]
	v_pk_mul_f32 v[116:117], v[116:117], v[112:113]
	v_pk_mul_f32 v[118:119], v[118:119], v[114:115]
	v_pk_fma_f32 v[228:229], v[228:229], v[172:173], v[172:173] op_sel_hi:[1,0,0]
	v_pk_fma_f32 v[230:231], v[230:231], v[172:173], v[172:173] op_sel_hi:[1,0,0]
	v_pk_fma_f32 v[232:233], v[232:233], v[172:173], v[172:173] op_sel_hi:[1,0,0]
	v_pk_fma_f32 v[234:235], v[234:235], v[172:173], v[172:173] op_sel_hi:[1,0,0]
	v_rcp_f32_e32 v228, v228
	v_rcp_f32_e32 v229, v229
	v_rcp_f32_e32 v230, v230
	v_rcp_f32_e32 v231, v231
	v_rcp_f32_e32 v232, v232
	v_rcp_f32_e32 v233, v233
	v_rcp_f32_e32 v234, v234
	v_rcp_f32_e32 v235, v235
	v_pk_mul_f32 v[124:125], v[124:125], v[228:229]
	v_pk_mul_f32 v[126:127], v[126:127], v[230:231]
	v_pk_mul_f32 v[116:117], v[116:117], v[232:233]
	v_pk_mul_f32 v[118:119], v[118:119], v[234:235]
	v_cvt_pk_bf16_f32 v236, v124, v125
	v_cvt_pk_bf16_f32 v237, v126, v127
	v_cvt_pk_bf16_f32 v238, v116, v117
; __device__ __forceinline__ unsigned pk2(float lo, float hi) { f32x2_t v = {lo, hi}; bf16x2_t b = __builtin_convertvector(v, bf16x2_t); return __builtin_bit_cast(unsigned, b); }
; __device__ __forceinline__ float sigm(float x) { return frcp(1.f + fexp2(-LOG2E * x)); }
;   __device__ __forceinline__ void operator()(const pg8::f32x4 (&acc)[2][2][4][2], const pg8::Unit& u, int wr, int wc, int fr, int fq) const {
;     ...
;       for (int m = 0; m < 4; ++m) {
;         const float r = rs[m]; float v[8];
; #pragma unroll
;         for (int n = 0; n < 2; ++n)
; #pragma unroll
;           for (int c = 0; c < 4; ++c) { const float g = acc[ai][0][m][n][c] * r, uu = acc[ai][1][m][n][c] * r; v[4 * n + c] = g * sigm(g) * uu; }
;         u32x4 w; w.x = pk2(v[0], v[1]); w.y = pk2(v[2], v[3]); w.z = pk2(v[4], v[5]); w.w = pk2(v[6], v[7]);
;         *(u32x4*)(hbuf + (unsigned)(row0 + ai * 128 + m * 16) * DFF + col0) = w;
	v_cvt_pk_bf16_f32 v239, v118, v119
	s_nop 0
	global_store_dwordx4 v[240:241], v[236:239], off
	v_lshl_add_u64 v[240:241], v[240:241], 0, s[100:101]
	v_pk_mul_f32 v[228:229], v[108:109], v[190:191] op_sel_hi:[1,0]
	v_pk_mul_f32 v[230:231], v[110:111], v[190:191] op_sel_hi:[1,0]
	v_pk_mul_f32 v[232:233], v[104:105], v[190:191] op_sel_hi:[1,0]
	v_pk_mul_f32 v[234:235], v[106:107], v[190:191] op_sel_hi:[1,0]
	v_exp_f32_e32 v228, v228
	v_exp_f32_e32 v229, v229
	v_exp_f32_e32 v230, v230
	v_exp_f32_e32 v231, v231
	v_exp_f32_e32 v232, v232
	v_exp_f32_e32 v233, v233
	v_exp_f32_e32 v234, v234
	v_exp_f32_e32 v235, v235
	v_pk_mul_f32 v[108:109], v[108:109], v[100:101]
	v_pk_mul_f32 v[110:111], v[110:111], v[102:103]
	v_pk_mul_f32 v[104:105], v[104:105], v[96:97]
	v_pk_mul_f32 v[106:107], v[106:107], v[98:99]
	v_pk_fma_f32 v[228:229], v[228:229], v[174:175], v[174:175] op_sel_hi:[1,0,0]
	v_pk_fma_f32 v[230:231], v[230:231], v[174:175], v[174:175] op_sel_hi:[1,0,0]
	v_pk_fma_f32 v[232:233], v[232:233], v[174:175], v[174:175] op_sel_hi:[1,0,0]
	v_pk_fma_f32 v[234:235], v[234:235], v[174:175], v[174:175] op_sel_hi:[1,0,0]
	v_rcp_f32_e32 v228, v228
	v_rcp_f32_e32 v229, v229
	v_rcp_f32_e32 v230, v230
	v_rcp_f32_e32 v231, v231
	v_rcp_f32_e32 v232, v232
	v_rcp_f32_e32 v233, v233
	v_rcp_f32_e32 v234, v234
	v_rcp_f32_e32 v235, v235
	v_pk_mul_f32 v[108:109], v[108:109], v[228:229]
	v_pk_mul_f32 v[110:111], v[110:111], v[230:231]
	v_pk_mul_f32 v[104:105], v[104:105], v[232:233]
	v_pk_mul_f32 v[106:107], v[106:107], v[234:235]
	v_cvt_pk_bf16_f32 v236, v108, v109
	v_cvt_pk_bf16_f32 v237, v110, v111
	v_cvt_pk_bf16_f32 v238, v104, v105
	v_cvt_pk_bf16_f32 v239, v106, v107
	s_nop 0
	global_store_dwordx4 v[240:241], v[236:239], off
	v_lshl_add_u64 v[240:241], v[240:241], 0, s[100:101]
	v_pk_mul_f32 v[228:229], v[92:93], v[192:193] op_sel_hi:[1,0]
	v_pk_mul_f32 v[230:231], v[94:95], v[192:193] op_sel_hi:[1,0]
	v_pk_mul_f32 v[232:233], v[88:89], v[192:193] op_sel_hi:[1,0]
	v_pk_mul_f32 v[234:235], v[90:91], v[192:193] op_sel_hi:[1,0]
	v_exp_f32_e32 v228, v228
	v_exp_f32_e32 v229, v229
	v_exp_f32_e32 v230, v230
	v_exp_f32_e32 v231, v231
	v_exp_f32_e32 v232, v232
	v_exp_f32_e32 v233, v233
	v_exp_f32_e32 v234, v234
	v_exp_f32_e32 v235, v235
	v_pk_mul_f32 v[92:93], v[92:93], v[84:85]
	v_pk_mul_f32 v[94:95], v[94:95], v[86:87]
	v_pk_mul_f32 v[88:89], v[88:89], v[80:81]
	v_pk_mul_f32 v[90:91], v[90:91], v[82:83]
	v_pk_fma_f32 v[228:229], v[228:229], v[176:177], v[176:177] op_sel_hi:[1,0,0]
	v_pk_fma_f32 v[230:231], v[230:231], v[176:177], v[176:177] op_sel_hi:[1,0,0]
	v_pk_fma_f32 v[232:233], v[232:233], v[176:177], v[176:177] op_sel_hi:[1,0,0]
	v_pk_fma_f32 v[234:235], v[234:235], v[176:177], v[176:177] op_sel_hi:[1,0,0]
	v_rcp_f32_e32 v228, v228
	v_rcp_f32_e32 v229, v229
	v_rcp_f32_e32 v230, v230
	v_rcp_f32_e32 v231, v231
	v_rcp_f32_e32 v232, v232
	v_rcp_f32_e32 v233, v233
	v_rcp_f32_e32 v234, v234
	v_rcp_f32_e32 v235, v235
	v_pk_mul_f32 v[92:93], v[92:93], v[228:229]
	v_pk_mul_f32 v[94:95], v[94:95], v[230:231]
	v_pk_mul_f32 v[88:89], v[88:89], v[232:233]
	v_pk_mul_f32 v[90:91], v[90:91], v[234:235]
	v_cvt_pk_bf16_f32 v236, v92, v93
	v_cvt_pk_bf16_f32 v237, v94, v95
	v_cvt_pk_bf16_f32 v238, v88, v89
	v_cvt_pk_bf16_f32 v239, v90, v91
	s_nop 0
	global_store_dwordx4 v[240:241], v[236:239], off
	v_lshl_add_u64 v[240:241], v[240:241], 0, s[100:101]
	v_pk_mul_f32 v[228:229], v[76:77], v[194:195] op_sel_hi:[1,0]
	v_pk_mul_f32 v[230:231], v[78:79], v[194:195] op_sel_hi:[1,0]
	v_pk_mul_f32 v[232:233], v[72:73], v[194:195] op_sel_hi:[1,0]
	v_pk_mul_f32 v[234:235], v[74:75], v[194:195] op_sel_hi:[1,0]
	v_exp_f32_e32 v228, v228
	v_exp_f32_e32 v229, v229
	v_exp_f32_e32 v230, v230
	v_exp_f32_e32 v231, v231
	v_exp_f32_e32 v232, v232
	v_exp_f32_e32 v233, v233
	v_exp_f32_e32 v234, v234
	v_exp_f32_e32 v235, v235
	v_pk_mul_f32 v[76:77], v[76:77], v[68:69]
	v_pk_mul_f32 v[78:79], v[78:79], v[70:71]
	v_pk_mul_f32 v[72:73], v[72:73], v[64:65]
	v_pk_mul_f32 v[74:75], v[74:75], v[66:67]
	v_pk_fma_f32 v[228:229], v[228:229], v[178:179], v[178:179] op_sel_hi:[1,0,0]
	v_pk_fma_f32 v[230:231], v[230:231], v[178:179], v[178:179] op_sel_hi:[1,0,0]
	v_pk_fma_f32 v[232:233], v[232:233], v[178:179], v[178:179] op_sel_hi:[1,0,0]
	v_pk_fma_f32 v[234:235], v[234:235], v[178:179], v[178:179] op_sel_hi:[1,0,0]
	v_rcp_f32_e32 v228, v228
	v_rcp_f32_e32 v229, v229
	v_rcp_f32_e32 v230, v230
	v_rcp_f32_e32 v231, v231
	v_rcp_f32_e32 v232, v232
	v_rcp_f32_e32 v233, v233
	v_rcp_f32_e32 v234, v234
	v_rcp_f32_e32 v235, v235
	v_pk_mul_f32 v[76:77], v[76:77], v[228:229]
	v_pk_mul_f32 v[78:79], v[78:79], v[230:231]
	v_pk_mul_f32 v[72:73], v[72:73], v[232:233]
	v_pk_mul_f32 v[74:75], v[74:75], v[234:235]
	v_cvt_pk_bf16_f32 v236, v76, v77
	v_cvt_pk_bf16_f32 v237, v78, v79
	v_cvt_pk_bf16_f32 v238, v72, v73
	v_cvt_pk_bf16_f32 v239, v74, v75
	s_nop 0
	global_store_dwordx4 v[240:241], v[236:239], off
	v_pk_mul_f32 v[228:229], v[60:61], v[196:197] op_sel_hi:[1,0]
	v_pk_mul_f32 v[230:231], v[62:63], v[196:197] op_sel_hi:[1,0]
	v_pk_mul_f32 v[232:233], v[56:57], v[196:197] op_sel_hi:[1,0]
	v_pk_mul_f32 v[234:235], v[58:59], v[196:197] op_sel_hi:[1,0]
	v_exp_f32_e32 v228, v228
	v_exp_f32_e32 v229, v229
	v_exp_f32_e32 v230, v230
	v_exp_f32_e32 v231, v231
	v_exp_f32_e32 v232, v232
	v_exp_f32_e32 v233, v233
	v_exp_f32_e32 v234, v234
	v_exp_f32_e32 v235, v235
	v_pk_mul_f32 v[60:61], v[60:61], v[52:53]
	v_pk_mul_f32 v[62:63], v[62:63], v[54:55]
	v_pk_mul_f32 v[56:57], v[56:57], v[48:49]
	v_pk_mul_f32 v[58:59], v[58:59], v[50:51]
	v_pk_fma_f32 v[228:229], v[228:229], v[180:181], v[180:181] op_sel_hi:[1,0,0]
; __device__ __forceinline__ unsigned pk2(float lo, float hi) { f32x2_t v = {lo, hi}; bf16x2_t b = __builtin_convertvector(v, bf16x2_t); return __builtin_bit_cast(unsigned, b); }
; __device__ __forceinline__ float sigm(float x) { return frcp(1.f + fexp2(-LOG2E * x)); }
; #define PG8_BAR __builtin_amdgcn_s_barrier()
; template <class Epi, class Sched, bool ALIGN_EPI = false, bool SP2 = false, bool F16 = false, bool TOKPERM = false>
; __device__ __forceinline__ void gemm_phase(PG8_LAS unsigned char* lds, const Gemm g, const Sched& S, const Epi& E, int wv) {
;     ...
;         if (!has_next) break;
; #pragma unroll
;         for (int a = 0; a < 2; ++a)
; #pragma unroll
;             for (int b = 0; b < 2; ++b)
; #pragma unroll
;                 for (int m = 0; m < 4; ++m)
; #pragma unroll
;                     for (int n = 0; n < 2; ++n) acc[a][b][m][n] = (f32x4){0.f, 0.f, 0.f, 0.f};
;         cur = nxt; cA = nA; cB = nB; ++ui;
;         if constexpr (ALIGN_EPI) { if (wr == 1) PG8_BAR; }
;   __device__ __forceinline__ void operator()(const pg8::f32x4 (&acc)[2][2][4][2], const pg8::Unit& u, int wr, int wc, int fr, int fq) const {
;     ...
;       for (int m = 0; m < 4; ++m) {
;         const float r = rs[m]; float v[8];
; #pragma unroll
;         for (int n = 0; n < 2; ++n)
; #pragma unroll
;           for (int c = 0; c < 4; ++c) { const float g = acc[ai][0][m][n][c] * r, uu = acc[ai][1][m][n][c] * r; v[4 * n + c] = g * sigm(g) * uu; }
;         u32x4 w; w.x = pk2(v[0], v[1]); w.y = pk2(v[2], v[3]); w.z = pk2(v[4], v[5]); w.w = pk2(v[6], v[7]);
;         *(u32x4*)(hbuf + (unsigned)(row0 + ai * 128 + m * 16) * DFF + col0) = w;
;       }
	v_pk_fma_f32 v[230:231], v[230:231], v[180:181], v[180:181] op_sel_hi:[1,0,0]
	v_pk_fma_f32 v[232:233], v[232:233], v[180:181], v[180:181] op_sel_hi:[1,0,0]
	v_pk_fma_f32 v[234:235], v[234:235], v[180:181], v[180:181] op_sel_hi:[1,0,0]
	v_rcp_f32_e32 v228, v228
	v_rcp_f32_e32 v229, v229
	v_rcp_f32_e32 v230, v230
	v_rcp_f32_e32 v231, v231
	v_rcp_f32_e32 v232, v232
	v_rcp_f32_e32 v233, v233
	v_rcp_f32_e32 v234, v234
	v_rcp_f32_e32 v235, v235
	v_pk_mul_f32 v[60:61], v[60:61], v[228:229]
	v_pk_mul_f32 v[62:63], v[62:63], v[230:231]
	v_pk_mul_f32 v[56:57], v[56:57], v[232:233]
	v_pk_mul_f32 v[58:59], v[58:59], v[234:235]
	v_cvt_pk_bf16_f32 v236, v60, v61
	v_cvt_pk_bf16_f32 v237, v62, v63
	v_cvt_pk_bf16_f32 v238, v56, v57
	v_cvt_pk_bf16_f32 v239, v58, v59
	s_nop 0
	global_store_dwordx4 v[242:243], v[236:239], off
	v_lshl_add_u64 v[242:243], v[242:243], 0, s[100:101]
	v_pk_mul_f32 v[228:229], v[44:45], v[198:199] op_sel_hi:[1,0]
	v_pk_mul_f32 v[230:231], v[46:47], v[198:199] op_sel_hi:[1,0]
	v_pk_mul_f32 v[232:233], v[40:41], v[198:199] op_sel_hi:[1,0]
	v_pk_mul_f32 v[234:235], v[42:43], v[198:199] op_sel_hi:[1,0]
	v_exp_f32_e32 v228, v228
	v_exp_f32_e32 v229, v229
	v_exp_f32_e32 v230, v230
	v_exp_f32_e32 v231, v231
	v_exp_f32_e32 v232, v232
	v_exp_f32_e32 v233, v233
	v_exp_f32_e32 v234, v234
	v_exp_f32_e32 v235, v235
	v_pk_mul_f32 v[44:45], v[44:45], v[36:37]
	v_pk_mul_f32 v[46:47], v[46:47], v[38:39]
	v_pk_mul_f32 v[40:41], v[40:41], v[32:33]
	v_pk_mul_f32 v[42:43], v[42:43], v[34:35]
	v_pk_fma_f32 v[228:229], v[228:229], v[182:183], v[182:183] op_sel_hi:[1,0,0]
	v_pk_fma_f32 v[230:231], v[230:231], v[182:183], v[182:183] op_sel_hi:[1,0,0]
	v_pk_fma_f32 v[232:233], v[232:233], v[182:183], v[182:183] op_sel_hi:[1,0,0]
	v_pk_fma_f32 v[234:235], v[234:235], v[182:183], v[182:183] op_sel_hi:[1,0,0]
	v_rcp_f32_e32 v228, v228
	v_rcp_f32_e32 v229, v229
	v_rcp_f32_e32 v230, v230
	v_rcp_f32_e32 v231, v231
	v_rcp_f32_e32 v232, v232
	v_rcp_f32_e32 v233, v233
	v_rcp_f32_e32 v234, v234
	v_rcp_f32_e32 v235, v235
	v_pk_mul_f32 v[44:45], v[44:45], v[228:229]
	v_pk_mul_f32 v[46:47], v[46:47], v[230:231]
	v_pk_mul_f32 v[40:41], v[40:41], v[232:233]
	v_pk_mul_f32 v[42:43], v[42:43], v[234:235]
	v_cvt_pk_bf16_f32 v236, v44, v45
	v_cvt_pk_bf16_f32 v237, v46, v47
	v_cvt_pk_bf16_f32 v238, v40, v41
	v_cvt_pk_bf16_f32 v239, v42, v43
	s_nop 0
	global_store_dwordx4 v[242:243], v[236:239], off
	v_lshl_add_u64 v[242:243], v[242:243], 0, s[100:101]
	v_pk_mul_f32 v[228:229], v[28:29], v[200:201] op_sel_hi:[1,0]
	v_pk_mul_f32 v[230:231], v[30:31], v[200:201] op_sel_hi:[1,0]
	v_pk_mul_f32 v[232:233], v[24:25], v[200:201] op_sel_hi:[1,0]
	v_pk_mul_f32 v[234:235], v[26:27], v[200:201] op_sel_hi:[1,0]
	v_exp_f32_e32 v228, v228
	v_exp_f32_e32 v229, v229
	v_exp_f32_e32 v230, v230
	v_exp_f32_e32 v231, v231
	v_exp_f32_e32 v232, v232
	v_exp_f32_e32 v233, v233
	v_exp_f32_e32 v234, v234
	v_exp_f32_e32 v235, v235
	v_pk_mul_f32 v[28:29], v[28:29], v[20:21]
	v_pk_mul_f32 v[30:31], v[30:31], v[22:23]
	v_pk_mul_f32 v[24:25], v[24:25], v[16:17]
	v_pk_mul_f32 v[26:27], v[26:27], v[18:19]
	v_pk_fma_f32 v[228:229], v[228:229], v[184:185], v[184:185] op_sel_hi:[1,0,0]
	v_pk_fma_f32 v[230:231], v[230:231], v[184:185], v[184:185] op_sel_hi:[1,0,0]
	v_pk_fma_f32 v[232:233], v[232:233], v[184:185], v[184:185] op_sel_hi:[1,0,0]
	v_pk_fma_f32 v[234:235], v[234:235], v[184:185], v[184:185] op_sel_hi:[1,0,0]
	v_rcp_f32_e32 v228, v228
	v_rcp_f32_e32 v229, v229
	v_rcp_f32_e32 v230, v230
	v_rcp_f32_e32 v231, v231
	v_rcp_f32_e32 v232, v232
	v_rcp_f32_e32 v233, v233
	v_rcp_f32_e32 v234, v234
	v_rcp_f32_e32 v235, v235
	v_pk_mul_f32 v[28:29], v[28:29], v[228:229]
	v_pk_mul_f32 v[30:31], v[30:31], v[230:231]
	v_pk_mul_f32 v[24:25], v[24:25], v[232:233]
	v_pk_mul_f32 v[26:27], v[26:27], v[234:235]
	v_cvt_pk_bf16_f32 v236, v28, v29
	v_cvt_pk_bf16_f32 v237, v30, v31
	v_cvt_pk_bf16_f32 v238, v24, v25
	v_cvt_pk_bf16_f32 v239, v26, v27
	s_nop 0
	global_store_dwordx4 v[242:243], v[236:239], off
	v_lshl_add_u64 v[242:243], v[242:243], 0, s[100:101]
	v_pk_mul_f32 v[228:229], v[12:13], v[202:203] op_sel_hi:[1,0]
	v_pk_mul_f32 v[230:231], v[14:15], v[202:203] op_sel_hi:[1,0]
	v_pk_mul_f32 v[232:233], v[8:9], v[202:203] op_sel_hi:[1,0]
	v_pk_mul_f32 v[234:235], v[10:11], v[202:203] op_sel_hi:[1,0]
	v_exp_f32_e32 v228, v228
	v_exp_f32_e32 v229, v229
	v_exp_f32_e32 v230, v230
	v_exp_f32_e32 v231, v231
	v_exp_f32_e32 v232, v232
	v_exp_f32_e32 v233, v233
	v_exp_f32_e32 v234, v234
	v_exp_f32_e32 v235, v235
	v_pk_mul_f32 v[12:13], v[12:13], v[4:5]
	v_pk_mul_f32 v[14:15], v[14:15], v[6:7]
	v_pk_mul_f32 v[8:9], v[8:9], v[0:1]
	v_pk_mul_f32 v[10:11], v[10:11], v[2:3]
	v_pk_fma_f32 v[228:229], v[228:229], v[186:187], v[186:187] op_sel_hi:[1,0,0]
	v_pk_fma_f32 v[230:231], v[230:231], v[186:187], v[186:187] op_sel_hi:[1,0,0]
	v_pk_fma_f32 v[232:233], v[232:233], v[186:187], v[186:187] op_sel_hi:[1,0,0]
	v_pk_fma_f32 v[234:235], v[234:235], v[186:187], v[186:187] op_sel_hi:[1,0,0]
	v_rcp_f32_e32 v228, v228
	v_rcp_f32_e32 v229, v229
	v_rcp_f32_e32 v230, v230
	v_rcp_f32_e32 v231, v231
	v_rcp_f32_e32 v232, v232
	v_rcp_f32_e32 v233, v233
	v_rcp_f32_e32 v234, v234
	v_rcp_f32_e32 v235, v235
	v_pk_mul_f32 v[12:13], v[12:13], v[228:229]
	v_pk_mul_f32 v[14:15], v[14:15], v[230:231]
	v_pk_mul_f32 v[8:9], v[8:9], v[232:233]
	v_pk_mul_f32 v[10:11], v[10:11], v[234:235]
	v_cvt_pk_bf16_f32 v236, v12, v13
	v_cvt_pk_bf16_f32 v237, v14, v15
	v_cvt_pk_bf16_f32 v238, v8, v9
	v_cvt_pk_bf16_f32 v239, v10, v11
	s_nop 0
	global_store_dwordx4 v[242:243], v[236:239], off
	s_andn2_b64 vcc, exec, s[2:3]
	s_mov_b64 s[2:3], -1
	s_cbranch_vccnz .LBB0_177
	s_andn2_b64 vcc, exec, s[10:11]
	s_cbranch_vccnz .LBB0_176
	s_barrier
	s_branch .LBB0_176

; __device__ __forceinline__ unsigned pk2(float lo, float hi) { f32x2_t v = {lo, hi}; bf16x2_t b = __builtin_convertvector(v, bf16x2_t); return __builtin_bit_cast(unsigned, b); }
; __device__ __forceinline__ float sigm(float x) { return frcp(1.f + fexp2(-LOG2E * x)); }
;   __device__ __forceinline__ void operator()(const pg8::f32x4 (&acc)[2][2][4][2], const pg8::Unit& u, int wr, int wc, int fr, int fq) const {
;     int z; asm volatile("v_mov_b32 %0, 0" : "=v"(z));
;     const int row0 = u.pm * 256 + wr * 64 + fr + z, col0 = u.pn * 128 + wc * 32 + 8 * fq + z;
; #pragma unroll
;     for (int ai = 0; ai < 2; ++ai) {
;       float rs[4];
; #pragma unroll
;       for (int m = 0; m < 4; ++m) { const f32x4 a = *(const f32x4*)(ssq + (unsigned)(row0 + ai * 128 + m * 16) * 16 + 4 * fq); rs[m] = (a[0] + a[1]) + (a[2] + a[3]); }
; #pragma unroll
;       for (int m = 0; m < 4; ++m) { float v = rs[m]; v += __shfl_xor(v, 16); v += __shfl_xor(v, 32); rs[m] = rsqrtf(v * (1.f / 1024.f) + EPS); }
; #pragma unroll
;       for (int m = 0; m < 4; ++m) {
;         const float r = rs[m]; float v[8];
; #pragma unroll
;         for (int n = 0; n < 2; ++n)
; #pragma unroll
;           for (int c = 0; c < 4; ++c) { const float g = acc[ai][0][m][n][c] * r, uu = acc[ai][1][m][n][c] * r; v[4 * n + c] = g * sigm(g) * uu; }
;         u32x4 w; w.x = pk2(v[0], v[1]); w.y = pk2(v[2], v[3]); w.z = pk2(v[4], v[5]); w.w = pk2(v[6], v[7]);
;         *(u32x4*)(hbuf + (unsigned)(row0 + ai * 128 + m * 16) * DFF + col0) = w;
.LBB0_771:
	s_lshl_b32 s8, s8, 8
	s_mov_b32 s98, 0x3a800000
	s_mov_b32 s100, 0xb0000
	s_mov_b32 s101, 0
	v_add_u32_e32 v148, s8, v151
	v_lshlrev_b32_e32 v136, 4, v148
	v_lshl_add_u64 v[242:243], v[136:137], 2, v[138:139]
	global_load_dwordx4 v[172:175], v[242:243], off
	global_load_dwordx4 v[176:179], v[242:243], off offset:1024
	global_load_dwordx4 v[180:183], v[242:243], off offset:2048
	global_load_dwordx4 v[184:187], v[242:243], off offset:3072
	v_add_u32_e32 v136, 0x800, v136
	v_lshl_add_u64 v[242:243], v[136:137], 2, v[138:139]
	global_load_dwordx4 v[188:191], v[242:243], off
	global_load_dwordx4 v[192:195], v[242:243], off offset:1024
	global_load_dwordx4 v[196:199], v[242:243], off offset:2048
	global_load_dwordx4 v[200:203], v[242:243], off offset:3072
	v_lshl_or_b32 v152, s9, 7, v154
	v_mul_u32_u24_e32 v136, 0xb00, v148
	v_add_u32_e32 v136, v136, v152
	v_lshl_add_u64 v[240:241], v[136:137], 1, s[38:39]
	v_mov_b32_e32 v150, 0x358637bd
	v_lshl_add_u64 v[242:243], v[240:241], 0, s[100:101]
	s_mov_b32 s100, 0x16000
	s_waitcnt vmcnt(0)
	v_add_f32_e32 v204, v172, v173
	v_add_f32_e32 v228, v174, v175
	v_add_f32_e32 v205, v176, v177
	v_add_f32_e32 v229, v178, v179
	v_add_f32_e32 v206, v180, v181
	v_add_f32_e32 v230, v182, v183
	v_add_f32_e32 v207, v184, v185
	v_add_f32_e32 v231, v186, v187
	v_add_f32_e32 v208, v188, v189
	v_add_f32_e32 v232, v190, v191
	v_add_f32_e32 v209, v192, v193
	v_add_f32_e32 v233, v194, v195
	v_add_f32_e32 v210, v196, v197
	v_add_f32_e32 v234, v198, v199
	v_add_f32_e32 v211, v200, v201
	v_add_f32_e32 v235, v202, v203
	v_add_f32_e32 v204, v204, v228
	v_add_f32_e32 v205, v205, v229
	v_add_f32_e32 v206, v206, v230
	v_add_f32_e32 v207, v207, v231
	v_add_f32_e32 v208, v208, v232
	v_add_f32_e32 v209, v209, v233
	v_add_f32_e32 v210, v210, v234
	v_add_f32_e32 v211, v211, v235
	v_mov_b32_e32 v228, v204
	v_mov_b32_e32 v229, v205
	v_mov_b32_e32 v230, v206
	v_mov_b32_e32 v231, v207
	v_mov_b32_e32 v232, v208
	v_mov_b32_e32 v233, v209
	v_mov_b32_e32 v234, v210
	v_mov_b32_e32 v235, v211
	v_permlane16_swap_b32_e32 v204, v228
	v_permlane16_swap_b32_e32 v205, v229
	v_permlane16_swap_b32_e32 v206, v230
	v_permlane16_swap_b32_e32 v207, v231
	v_permlane16_swap_b32_e32 v208, v232
	v_permlane16_swap_b32_e32 v209, v233
	v_permlane16_swap_b32_e32 v210, v234
	v_permlane16_swap_b32_e32 v211, v235
	v_add_f32_e32 v204, v204, v228
	v_add_f32_e32 v205, v205, v229
	v_add_f32_e32 v206, v206, v230
	v_add_f32_e32 v207, v207, v231
	v_add_f32_e32 v208, v208, v232
	v_add_f32_e32 v209, v209, v233
	v_add_f32_e32 v210, v210, v234
	v_add_f32_e32 v211, v211, v235
	v_mov_b32_e32 v228, v204
	v_mov_b32_e32 v229, v205
	v_mov_b32_e32 v230, v206
	v_mov_b32_e32 v231, v207
	v_mov_b32_e32 v232, v208
	v_mov_b32_e32 v233, v209
	v_mov_b32_e32 v234, v210
	v_mov_b32_e32 v235, v211
	v_permlane32_swap_b32_e32 v204, v228
	v_permlane32_swap_b32_e32 v205, v229
	v_permlane32_swap_b32_e32 v206, v230
	v_permlane32_swap_b32_e32 v207, v231
	v_permlane32_swap_b32_e32 v208, v232
	v_permlane32_swap_b32_e32 v209, v233
	v_permlane32_swap_b32_e32 v210, v234
	v_permlane32_swap_b32_e32 v211, v235
	v_add_f32_e32 v204, v204, v228
	v_add_f32_e32 v205, v205, v229
	v_add_f32_e32 v206, v206, v230
	v_add_f32_e32 v207, v207, v231
	v_add_f32_e32 v208, v208, v232
	v_add_f32_e32 v209, v209, v233
	v_add_f32_e32 v210, v210, v234
	v_add_f32_e32 v211, v211, v235
	v_fma_f32 v172, v204, s98, v150
	v_fma_f32 v174, v205, s98, v150
	v_fma_f32 v176, v206, s98, v150
	v_fma_f32 v178, v207, s98, v150
	v_fma_f32 v180, v208, s98, v150
	v_fma_f32 v182, v209, s98, v150
	v_fma_f32 v184, v210, s98, v150
	v_fma_f32 v186, v211, s98, v150
	v_rsq_f32_e32 v188, v172
	v_rsq_f32_e32 v190, v174
	v_rsq_f32_e32 v192, v176
	v_rsq_f32_e32 v194, v178
	v_rsq_f32_e32 v196, v180
	v_rsq_f32_e32 v198, v182
	v_rsq_f32_e32 v200, v184
	v_rsq_f32_e32 v202, v186
	v_mul_f32_e32 v188, 0xbfb8aa3b, v188
	v_mul_f32_e32 v190, 0xbfb8aa3b, v190
	v_mul_f32_e32 v192, 0xbfb8aa3b, v192
	v_mul_f32_e32 v194, 0xbfb8aa3b, v194
	v_mul_f32_e32 v196, 0xbfb8aa3b, v196
	v_mul_f32_e32 v198, 0xbfb8aa3b, v198
	v_mul_f32_e32 v200, 0xbfb8aa3b, v200
	v_mul_f32_e32 v202, 0xbfb8aa3b, v202
	v_pk_mul_f32 v[228:229], v[124:125], v[188:189] op_sel_hi:[1,0]
	v_pk_mul_f32 v[230:231], v[126:127], v[188:189] op_sel_hi:[1,0]
	v_pk_mul_f32 v[232:233], v[116:117], v[188:189] op_sel_hi:[1,0]
	v_pk_mul_f32 v[234:235], v[118:119], v[188:189] op_sel_hi:[1,0]
	v_exp_f32_e32 v228, v228
	v_exp_f32_e32 v229, v229
	v_exp_f32_e32 v230, v230
	v_exp_f32_e32 v231, v231
	v_exp_f32_e32 v232, v232
	v_exp_f32_e32 v233, v233
	v_exp_f32_e32 v234, v234
	v_exp_f32_e32 v235, v235
	v_pk_mul_f32 v[124:125], v[124:125], v[120:121]
	v_pk_mul_f32 v[126:127], v[126:127], v[122:123]
	v_pk_mul_f32 v[116:117], v[116:117], v[112:113]
	v_pk_mul_f32 v[118:119], v[118:119], v[114:115]
	v_pk_fma_f32 v[228:229], v[228:229], v[172:173], v[172:173] op_sel_hi:[1,0,0]
	v_pk_fma_f32 v[230:231], v[230:231], v[172:173], v[172:173] op_sel_hi:[1,0,0]
	v_pk_fma_f32 v[232:233], v[232:233], v[172:173], v[172:173] op_sel_hi:[1,0,0]
	v_pk_fma_f32 v[234:235], v[234:235], v[172:173], v[172:173] op_sel_hi:[1,0,0]
	v_rcp_f32_e32 v228, v228
	v_rcp_f32_e32 v229, v229
	v_rcp_f32_e32 v230, v230
	v_rcp_f32_e32 v231, v231
	v_rcp_f32_e32 v232, v232
	v_rcp_f32_e32 v233, v233
	v_rcp_f32_e32 v234, v234
	v_rcp_f32_e32 v235, v235
	v_pk_mul_f32 v[124:125], v[124:125], v[228:229]
	v_pk_mul_f32 v[126:127], v[126:127], v[230:231]
	v_pk_mul_f32 v[116:117], v[116:117], v[232:233]
	v_pk_mul_f32 v[118:119], v[118:119], v[234:235]
	v_cvt_pk_bf16_f32 v236, v124, v125
	v_cvt_pk_bf16_f32 v237, v126, v127
	v_cvt_pk_bf16_f32 v238, v116, v117
; __device__ __forceinline__ unsigned pk2(float lo, float hi) { f32x2_t v = {lo, hi}; bf16x2_t b = __builtin_convertvector(v, bf16x2_t); return __builtin_bit_cast(unsigned, b); }
; __device__ __forceinline__ float sigm(float x) { return frcp(1.f + fexp2(-LOG2E * x)); }
;   __device__ __forceinline__ void operator()(const pg8::f32x4 (&acc)[2][2][4][2], const pg8::Unit& u, int wr, int wc, int fr, int fq) const {
;     ...
;       for (int m = 0; m < 4; ++m) {
;         const float r = rs[m]; float v[8];
; #pragma unroll
;         for (int n = 0; n < 2; ++n)
; #pragma unroll
;           for (int c = 0; c < 4; ++c) { const float g = acc[ai][0][m][n][c] * r, uu = acc[ai][1][m][n][c] * r; v[4 * n + c] = g * sigm(g) * uu; }
;         u32x4 w; w.x = pk2(v[0], v[1]); w.y = pk2(v[2], v[3]); w.z = pk2(v[4], v[5]); w.w = pk2(v[6], v[7]);
;         *(u32x4*)(hbuf + (unsigned)(row0 + ai * 128 + m * 16) * DFF + col0) = w;
	v_cvt_pk_bf16_f32 v239, v118, v119
	s_nop 0
	global_store_dwordx4 v[240:241], v[236:239], off
	v_lshl_add_u64 v[240:241], v[240:241], 0, s[100:101]
	v_pk_mul_f32 v[228:229], v[108:109], v[190:191] op_sel_hi:[1,0]
	v_pk_mul_f32 v[230:231], v[110:111], v[190:191] op_sel_hi:[1,0]
	v_pk_mul_f32 v[232:233], v[104:105], v[190:191] op_sel_hi:[1,0]
	v_pk_mul_f32 v[234:235], v[106:107], v[190:191] op_sel_hi:[1,0]
	v_exp_f32_e32 v228, v228
	v_exp_f32_e32 v229, v229
	v_exp_f32_e32 v230, v230
	v_exp_f32_e32 v231, v231
	v_exp_f32_e32 v232, v232
	v_exp_f32_e32 v233, v233
	v_exp_f32_e32 v234, v234
	v_exp_f32_e32 v235, v235
	v_pk_mul_f32 v[108:109], v[108:109], v[100:101]
	v_pk_mul_f32 v[110:111], v[110:111], v[102:103]
	v_pk_mul_f32 v[104:105], v[104:105], v[96:97]
	v_pk_mul_f32 v[106:107], v[106:107], v[98:99]
	v_pk_fma_f32 v[228:229], v[228:229], v[174:175], v[174:175] op_sel_hi:[1,0,0]
	v_pk_fma_f32 v[230:231], v[230:231], v[174:175], v[174:175] op_sel_hi:[1,0,0]
	v_pk_fma_f32 v[232:233], v[232:233], v[174:175], v[174:175] op_sel_hi:[1,0,0]
	v_pk_fma_f32 v[234:235], v[234:235], v[174:175], v[174:175] op_sel_hi:[1,0,0]
	v_rcp_f32_e32 v228, v228
	v_rcp_f32_e32 v229, v229
	v_rcp_f32_e32 v230, v230
	v_rcp_f32_e32 v231, v231
	v_rcp_f32_e32 v232, v232
	v_rcp_f32_e32 v233, v233
	v_rcp_f32_e32 v234, v234
	v_rcp_f32_e32 v235, v235
	v_pk_mul_f32 v[108:109], v[108:109], v[228:229]
	v_pk_mul_f32 v[110:111], v[110:111], v[230:231]
	v_pk_mul_f32 v[104:105], v[104:105], v[232:233]
	v_pk_mul_f32 v[106:107], v[106:107], v[234:235]
	v_cvt_pk_bf16_f32 v236, v108, v109
	v_cvt_pk_bf16_f32 v237, v110, v111
	v_cvt_pk_bf16_f32 v238, v104, v105
	v_cvt_pk_bf16_f32 v239, v106, v107
	s_nop 0
	global_store_dwordx4 v[240:241], v[236:239], off
	v_lshl_add_u64 v[240:241], v[240:241], 0, s[100:101]
	v_pk_mul_f32 v[228:229], v[92:93], v[192:193] op_sel_hi:[1,0]
	v_pk_mul_f32 v[230:231], v[94:95], v[192:193] op_sel_hi:[1,0]
	v_pk_mul_f32 v[232:233], v[88:89], v[192:193] op_sel_hi:[1,0]
	v_pk_mul_f32 v[234:235], v[90:91], v[192:193] op_sel_hi:[1,0]
	v_exp_f32_e32 v228, v228
	v_exp_f32_e32 v229, v229
	v_exp_f32_e32 v230, v230
	v_exp_f32_e32 v231, v231
	v_exp_f32_e32 v232, v232
	v_exp_f32_e32 v233, v233
	v_exp_f32_e32 v234, v234
	v_exp_f32_e32 v235, v235
	v_pk_mul_f32 v[92:93], v[92:93], v[84:85]
	v_pk_mul_f32 v[94:95], v[94:95], v[86:87]
	v_pk_mul_f32 v[88:89], v[88:89], v[80:81]
	v_pk_mul_f32 v[90:91], v[90:91], v[82:83]
	v_pk_fma_f32 v[228:229], v[228:229], v[176:177], v[176:177] op_sel_hi:[1,0,0]
	v_pk_fma_f32 v[230:231], v[230:231], v[176:177], v[176:177] op_sel_hi:[1,0,0]
	v_pk_fma_f32 v[232:233], v[232:233], v[176:177], v[176:177] op_sel_hi:[1,0,0]
	v_pk_fma_f32 v[234:235], v[234:235], v[176:177], v[176:177] op_sel_hi:[1,0,0]
	v_rcp_f32_e32 v228, v228
	v_rcp_f32_e32 v229, v229
	v_rcp_f32_e32 v230, v230
	v_rcp_f32_e32 v231, v231
	v_rcp_f32_e32 v232, v232
	v_rcp_f32_e32 v233, v233
	v_rcp_f32_e32 v234, v234
	v_rcp_f32_e32 v235, v235
	v_pk_mul_f32 v[92:93], v[92:93], v[228:229]
	v_pk_mul_f32 v[94:95], v[94:95], v[230:231]
	v_pk_mul_f32 v[88:89], v[88:89], v[232:233]
	v_pk_mul_f32 v[90:91], v[90:91], v[234:235]
	v_cvt_pk_bf16_f32 v236, v92, v93
	v_cvt_pk_bf16_f32 v237, v94, v95
	v_cvt_pk_bf16_f32 v238, v88, v89
	v_cvt_pk_bf16_f32 v239, v90, v91
	s_nop 0
	global_store_dwordx4 v[240:241], v[236:239], off
	v_lshl_add_u64 v[240:241], v[240:241], 0, s[100:101]
	v_pk_mul_f32 v[228:229], v[76:77], v[194:195] op_sel_hi:[1,0]
	v_pk_mul_f32 v[230:231], v[78:79], v[194:195] op_sel_hi:[1,0]
	v_pk_mul_f32 v[232:233], v[72:73], v[194:195] op_sel_hi:[1,0]
	v_pk_mul_f32 v[234:235], v[74:75], v[194:195] op_sel_hi:[1,0]
	v_exp_f32_e32 v228, v228
	v_exp_f32_e32 v229, v229
	v_exp_f32_e32 v230, v230
	v_exp_f32_e32 v231, v231
	v_exp_f32_e32 v232, v232
	v_exp_f32_e32 v233, v233
	v_exp_f32_e32 v234, v234
	v_exp_f32_e32 v235, v235
	v_pk_mul_f32 v[76:77], v[76:77], v[68:69]
	v_pk_mul_f32 v[78:79], v[78:79], v[70:71]
	v_pk_mul_f32 v[72:73], v[72:73], v[64:65]
	v_pk_mul_f32 v[74:75], v[74:75], v[66:67]
	v_pk_fma_f32 v[228:229], v[228:229], v[178:179], v[178:179] op_sel_hi:[1,0,0]
	v_pk_fma_f32 v[230:231], v[230:231], v[178:179], v[178:179] op_sel_hi:[1,0,0]
	v_pk_fma_f32 v[232:233], v[232:233], v[178:179], v[178:179] op_sel_hi:[1,0,0]
	v_pk_fma_f32 v[234:235], v[234:235], v[178:179], v[178:179] op_sel_hi:[1,0,0]
	v_rcp_f32_e32 v228, v228
	v_rcp_f32_e32 v229, v229
	v_rcp_f32_e32 v230, v230
	v_rcp_f32_e32 v231, v231
	v_rcp_f32_e32 v232, v232
	v_rcp_f32_e32 v233, v233
	v_rcp_f32_e32 v234, v234
	v_rcp_f32_e32 v235, v235
	v_pk_mul_f32 v[76:77], v[76:77], v[228:229]
	v_pk_mul_f32 v[78:79], v[78:79], v[230:231]
	v_pk_mul_f32 v[72:73], v[72:73], v[232:233]
	v_pk_mul_f32 v[74:75], v[74:75], v[234:235]
	v_cvt_pk_bf16_f32 v236, v76, v77
	v_cvt_pk_bf16_f32 v237, v78, v79
	v_cvt_pk_bf16_f32 v238, v72, v73
	v_cvt_pk_bf16_f32 v239, v74, v75
	s_nop 0
	global_store_dwordx4 v[240:241], v[236:239], off
	v_pk_mul_f32 v[228:229], v[60:61], v[196:197] op_sel_hi:[1,0]
	v_pk_mul_f32 v[230:231], v[62:63], v[196:197] op_sel_hi:[1,0]
	v_pk_mul_f32 v[232:233], v[56:57], v[196:197] op_sel_hi:[1,0]
	v_pk_mul_f32 v[234:235], v[58:59], v[196:197] op_sel_hi:[1,0]
	v_exp_f32_e32 v228, v228
	v_exp_f32_e32 v229, v229
	v_exp_f32_e32 v230, v230
	v_exp_f32_e32 v231, v231
	v_exp_f32_e32 v232, v232
	v_exp_f32_e32 v233, v233
	v_exp_f32_e32 v234, v234
	v_exp_f32_e32 v235, v235
	v_pk_mul_f32 v[60:61], v[60:61], v[52:53]
	v_pk_mul_f32 v[62:63], v[62:63], v[54:55]
	v_pk_mul_f32 v[56:57], v[56:57], v[48:49]
	v_pk_mul_f32 v[58:59], v[58:59], v[50:51]
	v_pk_fma_f32 v[228:229], v[228:229], v[180:181], v[180:181] op_sel_hi:[1,0,0]
; __device__ __forceinline__ unsigned pk2(float lo, float hi) { f32x2_t v = {lo, hi}; bf16x2_t b = __builtin_convertvector(v, bf16x2_t); return __builtin_bit_cast(unsigned, b); }
; __device__ __forceinline__ float sigm(float x) { return frcp(1.f + fexp2(-LOG2E * x)); }
; #define PG8_BAR __builtin_amdgcn_s_barrier()
; template <class Epi, class Sched, bool ALIGN_EPI = false, bool SP2 = false, bool F16 = false, bool TOKPERM = false>
; __device__ __forceinline__ void gemm_phase(PG8_LAS unsigned char* lds, const Gemm g, const Sched& S, const Epi& E, int wv) {
;     ...
;         if (!has_next) break;
; #pragma unroll
;         for (int a = 0; a < 2; ++a)
; #pragma unroll
;             for (int b = 0; b < 2; ++b)
; #pragma unroll
;                 for (int m = 0; m < 4; ++m)
; #pragma unroll
;                     for (int n = 0; n < 2; ++n) acc[a][b][m][n] = (f32x4){0.f, 0.f, 0.f, 0.f};
;         cur = nxt; cA = nA; cB = nB; ++ui;
;         if constexpr (ALIGN_EPI) { if (wr == 1) PG8_BAR; }
;   __device__ __forceinline__ void operator()(const pg8::f32x4 (&acc)[2][2][4][2], const pg8::Unit& u, int wr, int wc, int fr, int fq) const {
;     ...
;       for (int m = 0; m < 4; ++m) {
;         const float r = rs[m]; float v[8];
; #pragma unroll
;         for (int n = 0; n < 2; ++n)
; #pragma unroll
;           for (int c = 0; c < 4; ++c) { const float g = acc[ai][0][m][n][c] * r, uu = acc[ai][1][m][n][c] * r; v[4 * n + c] = g * sigm(g) * uu; }
;         u32x4 w; w.x = pk2(v[0], v[1]); w.y = pk2(v[2], v[3]); w.z = pk2(v[4], v[5]); w.w = pk2(v[6], v[7]);
;         *(u32x4*)(hbuf + (unsigned)(row0 + ai * 128 + m * 16) * DFF + col0) = w;
;       }
	v_pk_fma_f32 v[230:231], v[230:231], v[180:181], v[180:181] op_sel_hi:[1,0,0]
	v_pk_fma_f32 v[232:233], v[232:233], v[180:181], v[180:181] op_sel_hi:[1,0,0]
	v_pk_fma_f32 v[234:235], v[234:235], v[180:181], v[180:181] op_sel_hi:[1,0,0]
	v_rcp_f32_e32 v228, v228
	v_rcp_f32_e32 v229, v229
	v_rcp_f32_e32 v230, v230
	v_rcp_f32_e32 v231, v231
	v_rcp_f32_e32 v232, v232
	v_rcp_f32_e32 v233, v233
	v_rcp_f32_e32 v234, v234
	v_rcp_f32_e32 v235, v235
	v_pk_mul_f32 v[60:61], v[60:61], v[228:229]
	v_pk_mul_f32 v[62:63], v[62:63], v[230:231]
	v_pk_mul_f32 v[56:57], v[56:57], v[232:233]
	v_pk_mul_f32 v[58:59], v[58:59], v[234:235]
	v_cvt_pk_bf16_f32 v236, v60, v61
	v_cvt_pk_bf16_f32 v237, v62, v63
	v_cvt_pk_bf16_f32 v238, v56, v57
	v_cvt_pk_bf16_f32 v239, v58, v59
	s_nop 0
	global_store_dwordx4 v[242:243], v[236:239], off
	v_lshl_add_u64 v[242:243], v[242:243], 0, s[100:101]
	v_pk_mul_f32 v[228:229], v[44:45], v[198:199] op_sel_hi:[1,0]
	v_pk_mul_f32 v[230:231], v[46:47], v[198:199] op_sel_hi:[1,0]
	v_pk_mul_f32 v[232:233], v[40:41], v[198:199] op_sel_hi:[1,0]
	v_pk_mul_f32 v[234:235], v[42:43], v[198:199] op_sel_hi:[1,0]
	v_exp_f32_e32 v228, v228
	v_exp_f32_e32 v229, v229
	v_exp_f32_e32 v230, v230
	v_exp_f32_e32 v231, v231
	v_exp_f32_e32 v232, v232
	v_exp_f32_e32 v233, v233
	v_exp_f32_e32 v234, v234
	v_exp_f32_e32 v235, v235
	v_pk_mul_f32 v[44:45], v[44:45], v[36:37]
	v_pk_mul_f32 v[46:47], v[46:47], v[38:39]
	v_pk_mul_f32 v[40:41], v[40:41], v[32:33]
	v_pk_mul_f32 v[42:43], v[42:43], v[34:35]
	v_pk_fma_f32 v[228:229], v[228:229], v[182:183], v[182:183] op_sel_hi:[1,0,0]
	v_pk_fma_f32 v[230:231], v[230:231], v[182:183], v[182:183] op_sel_hi:[1,0,0]
	v_pk_fma_f32 v[232:233], v[232:233], v[182:183], v[182:183] op_sel_hi:[1,0,0]
	v_pk_fma_f32 v[234:235], v[234:235], v[182:183], v[182:183] op_sel_hi:[1,0,0]
	v_rcp_f32_e32 v228, v228
	v_rcp_f32_e32 v229, v229
	v_rcp_f32_e32 v230, v230
	v_rcp_f32_e32 v231, v231
	v_rcp_f32_e32 v232, v232
	v_rcp_f32_e32 v233, v233
	v_rcp_f32_e32 v234, v234
	v_rcp_f32_e32 v235, v235
	v_pk_mul_f32 v[44:45], v[44:45], v[228:229]
	v_pk_mul_f32 v[46:47], v[46:47], v[230:231]
	v_pk_mul_f32 v[40:41], v[40:41], v[232:233]
	v_pk_mul_f32 v[42:43], v[42:43], v[234:235]
	v_cvt_pk_bf16_f32 v236, v44, v45
	v_cvt_pk_bf16_f32 v237, v46, v47
	v_cvt_pk_bf16_f32 v238, v40, v41
	v_cvt_pk_bf16_f32 v239, v42, v43
	s_nop 0
	global_store_dwordx4 v[242:243], v[236:239], off
	v_lshl_add_u64 v[242:243], v[242:243], 0, s[100:101]
	v_pk_mul_f32 v[228:229], v[28:29], v[200:201] op_sel_hi:[1,0]
	v_pk_mul_f32 v[230:231], v[30:31], v[200:201] op_sel_hi:[1,0]
	v_pk_mul_f32 v[232:233], v[24:25], v[200:201] op_sel_hi:[1,0]
	v_pk_mul_f32 v[234:235], v[26:27], v[200:201] op_sel_hi:[1,0]
	v_exp_f32_e32 v228, v228
	v_exp_f32_e32 v229, v229
	v_exp_f32_e32 v230, v230
	v_exp_f32_e32 v231, v231
	v_exp_f32_e32 v232, v232
	v_exp_f32_e32 v233, v233
	v_exp_f32_e32 v234, v234
	v_exp_f32_e32 v235, v235
	v_pk_mul_f32 v[28:29], v[28:29], v[20:21]
	v_pk_mul_f32 v[30:31], v[30:31], v[22:23]
	v_pk_mul_f32 v[24:25], v[24:25], v[16:17]
	v_pk_mul_f32 v[26:27], v[26:27], v[18:19]
	v_pk_fma_f32 v[228:229], v[228:229], v[184:185], v[184:185] op_sel_hi:[1,0,0]
	v_pk_fma_f32 v[230:231], v[230:231], v[184:185], v[184:185] op_sel_hi:[1,0,0]
	v_pk_fma_f32 v[232:233], v[232:233], v[184:185], v[184:185] op_sel_hi:[1,0,0]
	v_pk_fma_f32 v[234:235], v[234:235], v[184:185], v[184:185] op_sel_hi:[1,0,0]
	v_rcp_f32_e32 v228, v228
	v_rcp_f32_e32 v229, v229
	v_rcp_f32_e32 v230, v230
	v_rcp_f32_e32 v231, v231
	v_rcp_f32_e32 v232, v232
	v_rcp_f32_e32 v233, v233
	v_rcp_f32_e32 v234, v234
	v_rcp_f32_e32 v235, v235
	v_pk_mul_f32 v[28:29], v[28:29], v[228:229]
	v_pk_mul_f32 v[30:31], v[30:31], v[230:231]
	v_pk_mul_f32 v[24:25], v[24:25], v[232:233]
	v_pk_mul_f32 v[26:27], v[26:27], v[234:235]
	v_cvt_pk_bf16_f32 v236, v28, v29
	v_cvt_pk_bf16_f32 v237, v30, v31
	v_cvt_pk_bf16_f32 v238, v24, v25
	v_cvt_pk_bf16_f32 v239, v26, v27
	s_nop 0
	global_store_dwordx4 v[242:243], v[236:239], off
	v_lshl_add_u64 v[242:243], v[242:243], 0, s[100:101]
	v_pk_mul_f32 v[228:229], v[12:13], v[202:203] op_sel_hi:[1,0]
	v_pk_mul_f32 v[230:231], v[14:15], v[202:203] op_sel_hi:[1,0]
	v_pk_mul_f32 v[232:233], v[8:9], v[202:203] op_sel_hi:[1,0]
	v_pk_mul_f32 v[234:235], v[10:11], v[202:203] op_sel_hi:[1,0]
	v_exp_f32_e32 v228, v228
	v_exp_f32_e32 v229, v229
	v_exp_f32_e32 v230, v230
	v_exp_f32_e32 v231, v231
	v_exp_f32_e32 v232, v232
	v_exp_f32_e32 v233, v233
	v_exp_f32_e32 v234, v234
	v_exp_f32_e32 v235, v235
	v_pk_mul_f32 v[12:13], v[12:13], v[4:5]
	v_pk_mul_f32 v[14:15], v[14:15], v[6:7]
	v_pk_mul_f32 v[8:9], v[8:9], v[0:1]
	v_pk_mul_f32 v[10:11], v[10:11], v[2:3]
	v_pk_fma_f32 v[228:229], v[228:229], v[186:187], v[186:187] op_sel_hi:[1,0,0]
	v_pk_fma_f32 v[230:231], v[230:231], v[186:187], v[186:187] op_sel_hi:[1,0,0]
	v_pk_fma_f32 v[232:233], v[232:233], v[186:187], v[186:187] op_sel_hi:[1,0,0]
	v_pk_fma_f32 v[234:235], v[234:235], v[186:187], v[186:187] op_sel_hi:[1,0,0]
	v_rcp_f32_e32 v228, v228
	v_rcp_f32_e32 v229, v229
	v_rcp_f32_e32 v230, v230
	v_rcp_f32_e32 v231, v231
	v_rcp_f32_e32 v232, v232
	v_rcp_f32_e32 v233, v233
	v_rcp_f32_e32 v234, v234
	v_rcp_f32_e32 v235, v235
	v_pk_mul_f32 v[12:13], v[12:13], v[228:229]
	v_pk_mul_f32 v[14:15], v[14:15], v[230:231]
	v_pk_mul_f32 v[8:9], v[8:9], v[232:233]
	v_pk_mul_f32 v[10:11], v[10:11], v[234:235]
	v_cvt_pk_bf16_f32 v236, v12, v13
	v_cvt_pk_bf16_f32 v237, v14, v15
	v_cvt_pk_bf16_f32 v238, v8, v9
	v_cvt_pk_bf16_f32 v239, v10, v11
	s_nop 0
	global_store_dwordx4 v[242:243], v[236:239], off
	s_andn2_b64 vcc, exec, s[6:7]
	s_mov_b64 s[6:7], -1
	s_cbranch_vccnz .LBB0_764
	s_andn2_b64 vcc, exec, s[14:15]
	s_cbranch_vccnz .LBB0_763
	s_barrier
	s_branch .LBB0_763

; __device__ __forceinline__ unsigned pk2(float lo, float hi) { f32x2_t v = {lo, hi}; bf16x2_t b = __builtin_convertvector(v, bf16x2_t); return __builtin_bit_cast(unsigned, b); }
; __device__ __forceinline__ float sigm(float x) { return frcp(1.f + fexp2(-LOG2E * x)); }
;   __device__ __forceinline__ void operator()(const pg8::f32x4 (&acc)[2][2][4][2], const pg8::Unit& u, int wr, int wc, int fr, int fq) const {
;     int z; asm volatile("v_mov_b32 %0, 0" : "=v"(z));
;     const int row0 = u.pm * 256 + wr * 64 + fr + z, col0 = u.pn * 128 + wc * 32 + 8 * fq + z;
; #pragma unroll
;     for (int ai = 0; ai < 2; ++ai) {
;       float rs[4];
; #pragma unroll
;       for (int m = 0; m < 4; ++m) { const f32x4 a = *(const f32x4*)(ssq + (unsigned)(row0 + ai * 128 + m * 16) * 16 + 4 * fq); rs[m] = (a[0] + a[1]) + (a[2] + a[3]); }
; #pragma unroll
;       for (int m = 0; m < 4; ++m) { float v = rs[m]; v += __shfl_xor(v, 16); v += __shfl_xor(v, 32); rs[m] = rsqrtf(v * (1.f / 1024.f) + EPS); }
; #pragma unroll
;       for (int m = 0; m < 4; ++m) {
;         const float r = rs[m]; float v[8];
; #pragma unroll
;         for (int n = 0; n < 2; ++n)
; #pragma unroll
;           for (int c = 0; c < 4; ++c) { const float g = acc[ai][0][m][n][c] * r, uu = acc[ai][1][m][n][c] * r; v[4 * n + c] = g * sigm(g) * uu; }
;         u32x4 w; w.x = pk2(v[0], v[1]); w.y = pk2(v[2], v[3]); w.z = pk2(v[4], v[5]); w.w = pk2(v[6], v[7]);
;         *(u32x4*)(hbuf + (unsigned)(row0 + ai * 128 + m * 16) * DFF + col0) = w;
.LBB0_1610:
	s_lshl_b32 s6, s6, 8
	s_mov_b32 s98, 0x3a800000
	s_mov_b32 s100, 0xb0000
	s_mov_b32 s101, 0
	v_add_u32_e32 v148, s6, v151
	v_lshlrev_b32_e32 v136, 4, v148
	v_lshl_add_u64 v[242:243], v[136:137], 2, v[138:139]
	global_load_dwordx4 v[172:175], v[242:243], off
	global_load_dwordx4 v[176:179], v[242:243], off offset:1024
	global_load_dwordx4 v[180:183], v[242:243], off offset:2048
	global_load_dwordx4 v[184:187], v[242:243], off offset:3072
	v_add_u32_e32 v136, 0x800, v136
	v_lshl_add_u64 v[242:243], v[136:137], 2, v[138:139]
	global_load_dwordx4 v[188:191], v[242:243], off
	global_load_dwordx4 v[192:195], v[242:243], off offset:1024
	global_load_dwordx4 v[196:199], v[242:243], off offset:2048
	global_load_dwordx4 v[200:203], v[242:243], off offset:3072
	v_lshl_or_b32 v152, s7, 7, v154
	v_mul_u32_u24_e32 v136, 0xb00, v148
	v_add_u32_e32 v136, v136, v152
	v_lshl_add_u64 v[240:241], v[136:137], 1, s[38:39]
	v_mov_b32_e32 v150, 0x358637bd
	v_lshl_add_u64 v[242:243], v[240:241], 0, s[100:101]
	s_mov_b32 s100, 0x16000
	s_waitcnt vmcnt(0)
	v_add_f32_e32 v204, v172, v173
	v_add_f32_e32 v228, v174, v175
	v_add_f32_e32 v205, v176, v177
	v_add_f32_e32 v229, v178, v179
	v_add_f32_e32 v206, v180, v181
	v_add_f32_e32 v230, v182, v183
	v_add_f32_e32 v207, v184, v185
	v_add_f32_e32 v231, v186, v187
	v_add_f32_e32 v208, v188, v189
	v_add_f32_e32 v232, v190, v191
	v_add_f32_e32 v209, v192, v193
	v_add_f32_e32 v233, v194, v195
	v_add_f32_e32 v210, v196, v197
	v_add_f32_e32 v234, v198, v199
	v_add_f32_e32 v211, v200, v201
	v_add_f32_e32 v235, v202, v203
	v_add_f32_e32 v204, v204, v228
	v_add_f32_e32 v205, v205, v229
	v_add_f32_e32 v206, v206, v230
	v_add_f32_e32 v207, v207, v231
	v_add_f32_e32 v208, v208, v232
	v_add_f32_e32 v209, v209, v233
	v_add_f32_e32 v210, v210, v234
	v_add_f32_e32 v211, v211, v235
	v_mov_b32_e32 v228, v204
	v_mov_b32_e32 v229, v205
	v_mov_b32_e32 v230, v206
	v_mov_b32_e32 v231, v207
	v_mov_b32_e32 v232, v208
	v_mov_b32_e32 v233, v209
	v_mov_b32_e32 v234, v210
	v_mov_b32_e32 v235, v211
	v_permlane16_swap_b32_e32 v204, v228
	v_permlane16_swap_b32_e32 v205, v229
	v_permlane16_swap_b32_e32 v206, v230
	v_permlane16_swap_b32_e32 v207, v231
	v_permlane16_swap_b32_e32 v208, v232
	v_permlane16_swap_b32_e32 v209, v233
	v_permlane16_swap_b32_e32 v210, v234
	v_permlane16_swap_b32_e32 v211, v235
	v_add_f32_e32 v204, v204, v228
	v_add_f32_e32 v205, v205, v229
	v_add_f32_e32 v206, v206, v230
	v_add_f32_e32 v207, v207, v231
	v_add_f32_e32 v208, v208, v232
	v_add_f32_e32 v209, v209, v233
	v_add_f32_e32 v210, v210, v234
	v_add_f32_e32 v211, v211, v235
	v_mov_b32_e32 v228, v204
	v_mov_b32_e32 v229, v205
	v_mov_b32_e32 v230, v206
	v_mov_b32_e32 v231, v207
	v_mov_b32_e32 v232, v208
	v_mov_b32_e32 v233, v209
	v_mov_b32_e32 v234, v210
	v_mov_b32_e32 v235, v211
	v_permlane32_swap_b32_e32 v204, v228
	v_permlane32_swap_b32_e32 v205, v229
	v_permlane32_swap_b32_e32 v206, v230
	v_permlane32_swap_b32_e32 v207, v231
	v_permlane32_swap_b32_e32 v208, v232
	v_permlane32_swap_b32_e32 v209, v233
	v_permlane32_swap_b32_e32 v210, v234
	v_permlane32_swap_b32_e32 v211, v235
	v_add_f32_e32 v204, v204, v228
	v_add_f32_e32 v205, v205, v229
	v_add_f32_e32 v206, v206, v230
	v_add_f32_e32 v207, v207, v231
	v_add_f32_e32 v208, v208, v232
	v_add_f32_e32 v209, v209, v233
	v_add_f32_e32 v210, v210, v234
	v_add_f32_e32 v211, v211, v235
	v_fma_f32 v172, v204, s98, v150
	v_fma_f32 v174, v205, s98, v150
	v_fma_f32 v176, v206, s98, v150
	v_fma_f32 v178, v207, s98, v150
	v_fma_f32 v180, v208, s98, v150
	v_fma_f32 v182, v209, s98, v150
	v_fma_f32 v184, v210, s98, v150
	v_fma_f32 v186, v211, s98, v150
	v_rsq_f32_e32 v188, v172
	v_rsq_f32_e32 v190, v174
	v_rsq_f32_e32 v192, v176
	v_rsq_f32_e32 v194, v178
	v_rsq_f32_e32 v196, v180
	v_rsq_f32_e32 v198, v182
	v_rsq_f32_e32 v200, v184
	v_rsq_f32_e32 v202, v186
	v_mul_f32_e32 v188, 0xbfb8aa3b, v188
	v_mul_f32_e32 v190, 0xbfb8aa3b, v190
	v_mul_f32_e32 v192, 0xbfb8aa3b, v192
	v_mul_f32_e32 v194, 0xbfb8aa3b, v194
	v_mul_f32_e32 v196, 0xbfb8aa3b, v196
	v_mul_f32_e32 v198, 0xbfb8aa3b, v198
	v_mul_f32_e32 v200, 0xbfb8aa3b, v200
	v_mul_f32_e32 v202, 0xbfb8aa3b, v202
	v_pk_mul_f32 v[228:229], v[124:125], v[188:189] op_sel_hi:[1,0]
	v_pk_mul_f32 v[230:231], v[126:127], v[188:189] op_sel_hi:[1,0]
	v_pk_mul_f32 v[232:233], v[116:117], v[188:189] op_sel_hi:[1,0]
	v_pk_mul_f32 v[234:235], v[118:119], v[188:189] op_sel_hi:[1,0]
	v_exp_f32_e32 v228, v228
	v_exp_f32_e32 v229, v229
	v_exp_f32_e32 v230, v230
	v_exp_f32_e32 v231, v231
	v_exp_f32_e32 v232, v232
	v_exp_f32_e32 v233, v233
	v_exp_f32_e32 v234, v234
	v_exp_f32_e32 v235, v235
	v_pk_mul_f32 v[124:125], v[124:125], v[120:121]
	v_pk_mul_f32 v[126:127], v[126:127], v[122:123]
	v_pk_mul_f32 v[116:117], v[116:117], v[112:113]
	v_pk_mul_f32 v[118:119], v[118:119], v[114:115]
	v_pk_fma_f32 v[228:229], v[228:229], v[172:173], v[172:173] op_sel_hi:[1,0,0]
	v_pk_fma_f32 v[230:231], v[230:231], v[172:173], v[172:173] op_sel_hi:[1,0,0]
	v_pk_fma_f32 v[232:233], v[232:233], v[172:173], v[172:173] op_sel_hi:[1,0,0]
	v_pk_fma_f32 v[234:235], v[234:235], v[172:173], v[172:173] op_sel_hi:[1,0,0]
	v_rcp_f32_e32 v228, v228
	v_rcp_f32_e32 v229, v229
	v_rcp_f32_e32 v230, v230
	v_rcp_f32_e32 v231, v231
	v_rcp_f32_e32 v232, v232
	v_rcp_f32_e32 v233, v233
	v_rcp_f32_e32 v234, v234
	v_rcp_f32_e32 v235, v235
	v_pk_mul_f32 v[124:125], v[124:125], v[228:229]
	v_pk_mul_f32 v[126:127], v[126:127], v[230:231]
	v_pk_mul_f32 v[116:117], v[116:117], v[232:233]
	v_pk_mul_f32 v[118:119], v[118:119], v[234:235]
	v_cvt_pk_bf16_f32 v236, v124, v125
	v_cvt_pk_bf16_f32 v237, v126, v127
	v_cvt_pk_bf16_f32 v238, v116, v117
; __device__ __forceinline__ unsigned pk2(float lo, float hi) { f32x2_t v = {lo, hi}; bf16x2_t b = __builtin_convertvector(v, bf16x2_t); return __builtin_bit_cast(unsigned, b); }
; __device__ __forceinline__ float sigm(float x) { return frcp(1.f + fexp2(-LOG2E * x)); }
;   __device__ __forceinline__ void operator()(const pg8::f32x4 (&acc)[2][2][4][2], const pg8::Unit& u, int wr, int wc, int fr, int fq) const {
;     ...
;       for (int m = 0; m < 4; ++m) {
;         const float r = rs[m]; float v[8];
; #pragma unroll
;         for (int n = 0; n < 2; ++n)
; #pragma unroll
;           for (int c = 0; c < 4; ++c) { const float g = acc[ai][0][m][n][c] * r, uu = acc[ai][1][m][n][c] * r; v[4 * n + c] = g * sigm(g) * uu; }
;         u32x4 w; w.x = pk2(v[0], v[1]); w.y = pk2(v[2], v[3]); w.z = pk2(v[4], v[5]); w.w = pk2(v[6], v[7]);
;         *(u32x4*)(hbuf + (unsigned)(row0 + ai * 128 + m * 16) * DFF + col0) = w;
	v_cvt_pk_bf16_f32 v239, v118, v119
	s_nop 0
	global_store_dwordx4 v[240:241], v[236:239], off
	v_lshl_add_u64 v[240:241], v[240:241], 0, s[100:101]
	v_pk_mul_f32 v[228:229], v[108:109], v[190:191] op_sel_hi:[1,0]
	v_pk_mul_f32 v[230:231], v[110:111], v[190:191] op_sel_hi:[1,0]
	v_pk_mul_f32 v[232:233], v[104:105], v[190:191] op_sel_hi:[1,0]
	v_pk_mul_f32 v[234:235], v[106:107], v[190:191] op_sel_hi:[1,0]
	v_exp_f32_e32 v228, v228
	v_exp_f32_e32 v229, v229
	v_exp_f32_e32 v230, v230
	v_exp_f32_e32 v231, v231
	v_exp_f32_e32 v232, v232
	v_exp_f32_e32 v233, v233
	v_exp_f32_e32 v234, v234
	v_exp_f32_e32 v235, v235
	v_pk_mul_f32 v[108:109], v[108:109], v[100:101]
	v_pk_mul_f32 v[110:111], v[110:111], v[102:103]
	v_pk_mul_f32 v[104:105], v[104:105], v[96:97]
	v_pk_mul_f32 v[106:107], v[106:107], v[98:99]
	v_pk_fma_f32 v[228:229], v[228:229], v[174:175], v[174:175] op_sel_hi:[1,0,0]
	v_pk_fma_f32 v[230:231], v[230:231], v[174:175], v[174:175] op_sel_hi:[1,0,0]
	v_pk_fma_f32 v[232:233], v[232:233], v[174:175], v[174:175] op_sel_hi:[1,0,0]
	v_pk_fma_f32 v[234:235], v[234:235], v[174:175], v[174:175] op_sel_hi:[1,0,0]
	v_rcp_f32_e32 v228, v228
	v_rcp_f32_e32 v229, v229
	v_rcp_f32_e32 v230, v230
	v_rcp_f32_e32 v231, v231
	v_rcp_f32_e32 v232, v232
	v_rcp_f32_e32 v233, v233
	v_rcp_f32_e32 v234, v234
	v_rcp_f32_e32 v235, v235
	v_pk_mul_f32 v[108:109], v[108:109], v[228:229]
	v_pk_mul_f32 v[110:111], v[110:111], v[230:231]
	v_pk_mul_f32 v[104:105], v[104:105], v[232:233]
	v_pk_mul_f32 v[106:107], v[106:107], v[234:235]
	v_cvt_pk_bf16_f32 v236, v108, v109
	v_cvt_pk_bf16_f32 v237, v110, v111
	v_cvt_pk_bf16_f32 v238, v104, v105
	v_cvt_pk_bf16_f32 v239, v106, v107
	s_nop 0
	global_store_dwordx4 v[240:241], v[236:239], off
	v_lshl_add_u64 v[240:241], v[240:241], 0, s[100:101]
	v_pk_mul_f32 v[228:229], v[92:93], v[192:193] op_sel_hi:[1,0]
	v_pk_mul_f32 v[230:231], v[94:95], v[192:193] op_sel_hi:[1,0]
	v_pk_mul_f32 v[232:233], v[88:89], v[192:193] op_sel_hi:[1,0]
	v_pk_mul_f32 v[234:235], v[90:91], v[192:193] op_sel_hi:[1,0]
	v_exp_f32_e32 v228, v228
	v_exp_f32_e32 v229, v229
	v_exp_f32_e32 v230, v230
	v_exp_f32_e32 v231, v231
	v_exp_f32_e32 v232, v232
	v_exp_f32_e32 v233, v233
	v_exp_f32_e32 v234, v234
	v_exp_f32_e32 v235, v235
	v_pk_mul_f32 v[92:93], v[92:93], v[84:85]
	v_pk_mul_f32 v[94:95], v[94:95], v[86:87]
	v_pk_mul_f32 v[88:89], v[88:89], v[80:81]
	v_pk_mul_f32 v[90:91], v[90:91], v[82:83]
	v_pk_fma_f32 v[228:229], v[228:229], v[176:177], v[176:177] op_sel_hi:[1,0,0]
	v_pk_fma_f32 v[230:231], v[230:231], v[176:177], v[176:177] op_sel_hi:[1,0,0]
	v_pk_fma_f32 v[232:233], v[232:233], v[176:177], v[176:177] op_sel_hi:[1,0,0]
	v_pk_fma_f32 v[234:235], v[234:235], v[176:177], v[176:177] op_sel_hi:[1,0,0]
	v_rcp_f32_e32 v228, v228
	v_rcp_f32_e32 v229, v229
	v_rcp_f32_e32 v230, v230
	v_rcp_f32_e32 v231, v231
	v_rcp_f32_e32 v232, v232
	v_rcp_f32_e32 v233, v233
	v_rcp_f32_e32 v234, v234
	v_rcp_f32_e32 v235, v235
	v_pk_mul_f32 v[92:93], v[92:93], v[228:229]
	v_pk_mul_f32 v[94:95], v[94:95], v[230:231]
	v_pk_mul_f32 v[88:89], v[88:89], v[232:233]
	v_pk_mul_f32 v[90:91], v[90:91], v[234:235]
	v_cvt_pk_bf16_f32 v236, v92, v93
	v_cvt_pk_bf16_f32 v237, v94, v95
	v_cvt_pk_bf16_f32 v238, v88, v89
	v_cvt_pk_bf16_f32 v239, v90, v91
	s_nop 0
	global_store_dwordx4 v[240:241], v[236:239], off
	v_lshl_add_u64 v[240:241], v[240:241], 0, s[100:101]
	v_pk_mul_f32 v[228:229], v[76:77], v[194:195] op_sel_hi:[1,0]
	v_pk_mul_f32 v[230:231], v[78:79], v[194:195] op_sel_hi:[1,0]
	v_pk_mul_f32 v[232:233], v[72:73], v[194:195] op_sel_hi:[1,0]
	v_pk_mul_f32 v[234:235], v[74:75], v[194:195] op_sel_hi:[1,0]
	v_exp_f32_e32 v228, v228
	v_exp_f32_e32 v229, v229
	v_exp_f32_e32 v230, v230
	v_exp_f32_e32 v231, v231
	v_exp_f32_e32 v232, v232
	v_exp_f32_e32 v233, v233
	v_exp_f32_e32 v234, v234
	v_exp_f32_e32 v235, v235
	v_pk_mul_f32 v[76:77], v[76:77], v[68:69]
	v_pk_mul_f32 v[78:79], v[78:79], v[70:71]
	v_pk_mul_f32 v[72:73], v[72:73], v[64:65]
	v_pk_mul_f32 v[74:75], v[74:75], v[66:67]
	v_pk_fma_f32 v[228:229], v[228:229], v[178:179], v[178:179] op_sel_hi:[1,0,0]
	v_pk_fma_f32 v[230:231], v[230:231], v[178:179], v[178:179] op_sel_hi:[1,0,0]
	v_pk_fma_f32 v[232:233], v[232:233], v[178:179], v[178:179] op_sel_hi:[1,0,0]
	v_pk_fma_f32 v[234:235], v[234:235], v[178:179], v[178:179] op_sel_hi:[1,0,0]
	v_rcp_f32_e32 v228, v228
	v_rcp_f32_e32 v229, v229
	v_rcp_f32_e32 v230, v230
	v_rcp_f32_e32 v231, v231
	v_rcp_f32_e32 v232, v232
	v_rcp_f32_e32 v233, v233
	v_rcp_f32_e32 v234, v234
	v_rcp_f32_e32 v235, v235
	v_pk_mul_f32 v[76:77], v[76:77], v[228:229]
	v_pk_mul_f32 v[78:79], v[78:79], v[230:231]
	v_pk_mul_f32 v[72:73], v[72:73], v[232:233]
	v_pk_mul_f32 v[74:75], v[74:75], v[234:235]
	v_cvt_pk_bf16_f32 v236, v76, v77
	v_cvt_pk_bf16_f32 v237, v78, v79
	v_cvt_pk_bf16_f32 v238, v72, v73
	v_cvt_pk_bf16_f32 v239, v74, v75
	s_nop 0
	global_store_dwordx4 v[240:241], v[236:239], off
	v_pk_mul_f32 v[228:229], v[60:61], v[196:197] op_sel_hi:[1,0]
	v_pk_mul_f32 v[230:231], v[62:63], v[196:197] op_sel_hi:[1,0]
	v_pk_mul_f32 v[232:233], v[56:57], v[196:197] op_sel_hi:[1,0]
	v_pk_mul_f32 v[234:235], v[58:59], v[196:197] op_sel_hi:[1,0]
	v_exp_f32_e32 v228, v228
	v_exp_f32_e32 v229, v229
	v_exp_f32_e32 v230, v230
	v_exp_f32_e32 v231, v231
	v_exp_f32_e32 v232, v232
	v_exp_f32_e32 v233, v233
	v_exp_f32_e32 v234, v234
	v_exp_f32_e32 v235, v235
	v_pk_mul_f32 v[60:61], v[60:61], v[52:53]
	v_pk_mul_f32 v[62:63], v[62:63], v[54:55]
	v_pk_mul_f32 v[56:57], v[56:57], v[48:49]
	v_pk_mul_f32 v[58:59], v[58:59], v[50:51]
	v_pk_fma_f32 v[228:229], v[228:229], v[180:181], v[180:181] op_sel_hi:[1,0,0]
; __device__ __forceinline__ unsigned pk2(float lo, float hi) { f32x2_t v = {lo, hi}; bf16x2_t b = __builtin_convertvector(v, bf16x2_t); return __builtin_bit_cast(unsigned, b); }
; __device__ __forceinline__ float sigm(float x) { return frcp(1.f + fexp2(-LOG2E * x)); }
; #define PG8_BAR __builtin_amdgcn_s_barrier()
; template <class Epi, class Sched, bool ALIGN_EPI = false, bool SP2 = false, bool F16 = false, bool TOKPERM = false>
; __device__ __forceinline__ void gemm_phase(PG8_LAS unsigned char* lds, const Gemm g, const Sched& S, const Epi& E, int wv) {
;     ...
;         if (!has_next) break;
; #pragma unroll
;         for (int a = 0; a < 2; ++a)
; #pragma unroll
;             for (int b = 0; b < 2; ++b)
; #pragma unroll
;                 for (int m = 0; m < 4; ++m)
; #pragma unroll
;                     for (int n = 0; n < 2; ++n) acc[a][b][m][n] = (f32x4){0.f, 0.f, 0.f, 0.f};
;         cur = nxt; cA = nA; cB = nB; ++ui;
;         if constexpr (ALIGN_EPI) { if (wr == 1) PG8_BAR; }
;   __device__ __forceinline__ void operator()(const pg8::f32x4 (&acc)[2][2][4][2], const pg8::Unit& u, int wr, int wc, int fr, int fq) const {
;     ...
;       for (int m = 0; m < 4; ++m) {
;         const float r = rs[m]; float v[8];
; #pragma unroll
;         for (int n = 0; n < 2; ++n)
; #pragma unroll
;           for (int c = 0; c < 4; ++c) { const float g = acc[ai][0][m][n][c] * r, uu = acc[ai][1][m][n][c] * r; v[4 * n + c] = g * sigm(g) * uu; }
;         u32x4 w; w.x = pk2(v[0], v[1]); w.y = pk2(v[2], v[3]); w.z = pk2(v[4], v[5]); w.w = pk2(v[6], v[7]);
;         *(u32x4*)(hbuf + (unsigned)(row0 + ai * 128 + m * 16) * DFF + col0) = w;
;       }
	v_pk_fma_f32 v[230:231], v[230:231], v[180:181], v[180:181] op_sel_hi:[1,0,0]
	v_pk_fma_f32 v[232:233], v[232:233], v[180:181], v[180:181] op_sel_hi:[1,0,0]
	v_pk_fma_f32 v[234:235], v[234:235], v[180:181], v[180:181] op_sel_hi:[1,0,0]
	v_rcp_f32_e32 v228, v228
	v_rcp_f32_e32 v229, v229
	v_rcp_f32_e32 v230, v230
	v_rcp_f32_e32 v231, v231
	v_rcp_f32_e32 v232, v232
	v_rcp_f32_e32 v233, v233
	v_rcp_f32_e32 v234, v234
	v_rcp_f32_e32 v235, v235
	v_pk_mul_f32 v[60:61], v[60:61], v[228:229]
	v_pk_mul_f32 v[62:63], v[62:63], v[230:231]
	v_pk_mul_f32 v[56:57], v[56:57], v[232:233]
	v_pk_mul_f32 v[58:59], v[58:59], v[234:235]
	v_cvt_pk_bf16_f32 v236, v60, v61
	v_cvt_pk_bf16_f32 v237, v62, v63
	v_cvt_pk_bf16_f32 v238, v56, v57
	v_cvt_pk_bf16_f32 v239, v58, v59
	s_nop 0
	global_store_dwordx4 v[242:243], v[236:239], off
	v_lshl_add_u64 v[242:243], v[242:243], 0, s[100:101]
	v_pk_mul_f32 v[228:229], v[44:45], v[198:199] op_sel_hi:[1,0]
	v_pk_mul_f32 v[230:231], v[46:47], v[198:199] op_sel_hi:[1,0]
	v_pk_mul_f32 v[232:233], v[40:41], v[198:199] op_sel_hi:[1,0]
	v_pk_mul_f32 v[234:235], v[42:43], v[198:199] op_sel_hi:[1,0]
	v_exp_f32_e32 v228, v228
	v_exp_f32_e32 v229, v229
	v_exp_f32_e32 v230, v230
	v_exp_f32_e32 v231, v231
	v_exp_f32_e32 v232, v232
	v_exp_f32_e32 v233, v233
	v_exp_f32_e32 v234, v234
	v_exp_f32_e32 v235, v235
	v_pk_mul_f32 v[44:45], v[44:45], v[36:37]
	v_pk_mul_f32 v[46:47], v[46:47], v[38:39]
	v_pk_mul_f32 v[40:41], v[40:41], v[32:33]
	v_pk_mul_f32 v[42:43], v[42:43], v[34:35]
	v_pk_fma_f32 v[228:229], v[228:229], v[182:183], v[182:183] op_sel_hi:[1,0,0]
	v_pk_fma_f32 v[230:231], v[230:231], v[182:183], v[182:183] op_sel_hi:[1,0,0]
	v_pk_fma_f32 v[232:233], v[232:233], v[182:183], v[182:183] op_sel_hi:[1,0,0]
	v_pk_fma_f32 v[234:235], v[234:235], v[182:183], v[182:183] op_sel_hi:[1,0,0]
	v_rcp_f32_e32 v228, v228
	v_rcp_f32_e32 v229, v229
	v_rcp_f32_e32 v230, v230
	v_rcp_f32_e32 v231, v231
	v_rcp_f32_e32 v232, v232
	v_rcp_f32_e32 v233, v233
	v_rcp_f32_e32 v234, v234
	v_rcp_f32_e32 v235, v235
	v_pk_mul_f32 v[44:45], v[44:45], v[228:229]
	v_pk_mul_f32 v[46:47], v[46:47], v[230:231]
	v_pk_mul_f32 v[40:41], v[40:41], v[232:233]
	v_pk_mul_f32 v[42:43], v[42:43], v[234:235]
	v_cvt_pk_bf16_f32 v236, v44, v45
	v_cvt_pk_bf16_f32 v237, v46, v47
	v_cvt_pk_bf16_f32 v238, v40, v41
	v_cvt_pk_bf16_f32 v239, v42, v43
	s_nop 0
	global_store_dwordx4 v[242:243], v[236:239], off
	v_lshl_add_u64 v[242:243], v[242:243], 0, s[100:101]
	v_pk_mul_f32 v[228:229], v[28:29], v[200:201] op_sel_hi:[1,0]
	v_pk_mul_f32 v[230:231], v[30:31], v[200:201] op_sel_hi:[1,0]
	v_pk_mul_f32 v[232:233], v[24:25], v[200:201] op_sel_hi:[1,0]
	v_pk_mul_f32 v[234:235], v[26:27], v[200:201] op_sel_hi:[1,0]
	v_exp_f32_e32 v228, v228
	v_exp_f32_e32 v229, v229
	v_exp_f32_e32 v230, v230
	v_exp_f32_e32 v231, v231
	v_exp_f32_e32 v232, v232
	v_exp_f32_e32 v233, v233
	v_exp_f32_e32 v234, v234
	v_exp_f32_e32 v235, v235
	v_pk_mul_f32 v[28:29], v[28:29], v[20:21]
	v_pk_mul_f32 v[30:31], v[30:31], v[22:23]
	v_pk_mul_f32 v[24:25], v[24:25], v[16:17]
	v_pk_mul_f32 v[26:27], v[26:27], v[18:19]
	v_pk_fma_f32 v[228:229], v[228:229], v[184:185], v[184:185] op_sel_hi:[1,0,0]
	v_pk_fma_f32 v[230:231], v[230:231], v[184:185], v[184:185] op_sel_hi:[1,0,0]
	v_pk_fma_f32 v[232:233], v[232:233], v[184:185], v[184:185] op_sel_hi:[1,0,0]
	v_pk_fma_f32 v[234:235], v[234:235], v[184:185], v[184:185] op_sel_hi:[1,0,0]
	v_rcp_f32_e32 v228, v228
	v_rcp_f32_e32 v229, v229
	v_rcp_f32_e32 v230, v230
	v_rcp_f32_e32 v231, v231
	v_rcp_f32_e32 v232, v232
	v_rcp_f32_e32 v233, v233
	v_rcp_f32_e32 v234, v234
	v_rcp_f32_e32 v235, v235
	v_pk_mul_f32 v[28:29], v[28:29], v[228:229]
	v_pk_mul_f32 v[30:31], v[30:31], v[230:231]
	v_pk_mul_f32 v[24:25], v[24:25], v[232:233]
	v_pk_mul_f32 v[26:27], v[26:27], v[234:235]
	v_cvt_pk_bf16_f32 v236, v28, v29
	v_cvt_pk_bf16_f32 v237, v30, v31
	v_cvt_pk_bf16_f32 v238, v24, v25
	v_cvt_pk_bf16_f32 v239, v26, v27
	s_nop 0
	global_store_dwordx4 v[242:243], v[236:239], off
	v_lshl_add_u64 v[242:243], v[242:243], 0, s[100:101]
	v_pk_mul_f32 v[228:229], v[12:13], v[202:203] op_sel_hi:[1,0]
	v_pk_mul_f32 v[230:231], v[14:15], v[202:203] op_sel_hi:[1,0]
	v_pk_mul_f32 v[232:233], v[8:9], v[202:203] op_sel_hi:[1,0]
	v_pk_mul_f32 v[234:235], v[10:11], v[202:203] op_sel_hi:[1,0]
	v_exp_f32_e32 v228, v228
	v_exp_f32_e32 v229, v229
	v_exp_f32_e32 v230, v230
	v_exp_f32_e32 v231, v231
	v_exp_f32_e32 v232, v232
	v_exp_f32_e32 v233, v233
	v_exp_f32_e32 v234, v234
	v_exp_f32_e32 v235, v235
	v_pk_mul_f32 v[12:13], v[12:13], v[4:5]
	v_pk_mul_f32 v[14:15], v[14:15], v[6:7]
	v_pk_mul_f32 v[8:9], v[8:9], v[0:1]
	v_pk_mul_f32 v[10:11], v[10:11], v[2:3]
	v_pk_fma_f32 v[228:229], v[228:229], v[186:187], v[186:187] op_sel_hi:[1,0,0]
	v_pk_fma_f32 v[230:231], v[230:231], v[186:187], v[186:187] op_sel_hi:[1,0,0]
	v_pk_fma_f32 v[232:233], v[232:233], v[186:187], v[186:187] op_sel_hi:[1,0,0]
	v_pk_fma_f32 v[234:235], v[234:235], v[186:187], v[186:187] op_sel_hi:[1,0,0]
	v_rcp_f32_e32 v228, v228
	v_rcp_f32_e32 v229, v229
	v_rcp_f32_e32 v230, v230
	v_rcp_f32_e32 v231, v231
	v_rcp_f32_e32 v232, v232
	v_rcp_f32_e32 v233, v233
	v_rcp_f32_e32 v234, v234
	v_rcp_f32_e32 v235, v235
	v_pk_mul_f32 v[12:13], v[12:13], v[228:229]
	v_pk_mul_f32 v[14:15], v[14:15], v[230:231]
	v_pk_mul_f32 v[8:9], v[8:9], v[232:233]
	v_pk_mul_f32 v[10:11], v[10:11], v[234:235]
	v_cvt_pk_bf16_f32 v236, v12, v13
	v_cvt_pk_bf16_f32 v237, v14, v15
	v_cvt_pk_bf16_f32 v238, v8, v9
	v_cvt_pk_bf16_f32 v239, v10, v11
	s_nop 0
	global_store_dwordx4 v[242:243], v[236:239], off
	s_andn2_b64 vcc, exec, s[4:5]
	s_mov_b64 s[4:5], -1
	s_cbranch_vccnz .LBB0_1603
	s_andn2_b64 vcc, exec, s[12:13]
	s_cbranch_vccnz .LBB0_1602
	s_barrier
	s_branch .LBB0_1602
